# SWA head loop: waves 4-7 offset by 44x64 cycles per unit (about half a head iteration) against their SIMD partner waves
# speedup vs baseline: 1.0045x; 1.0009x over previous
.LBB0_426:
	v_cndmask_b32_e64 v3, 0, 1, s[92:93]
	v_mov_b64_e32 v[0:1], s[10:11]
	v_readfirstlane_b32 s12, v3
	s_lshl_b32 s9, s12, 2
	s_or_b32 s9, s9, 2
	s_lshl_b32 s12, s12, 9
	s_add_u32 s12, s86, s12
	s_addc_u32 s13, s87, 0
	s_ashr_i32 s26, s8, 7
	s_bfe_u32 s24, s8, 0x60001
	s_ashr_i32 s27, s26, 31
	s_lshl_b64 s[28:29], s[26:27], 13
	s_lshl_b32 s14, s24, 7
	s_or_b32 s28, s28, s14
	s_lshl_b32 s25, s26, 13
	v_lshl_add_u64 v[126:127], s[28:29], 0, v[114:115]
	s_or_b32 s14, s25, s14
	v_or_b32_e32 v4, v126, v112
	s_addk_i32 s14, 0xff80
	s_and_b32 s15, s8, 1
	v_mad_u64_u32 v[4:5], s[28:29], v4, s62, v[0:1]
	v_add_u32_e32 v6, s14, v136
	v_mad_i32_i24 v5, v127, s62, v5
	s_lshl_b32 s94, s15, 9
	v_max_i32_e32 v6, s25, v6
	v_lshl_add_u64 v[4:5], v[4:5], 0, s[94:95]
	v_mad_i64_i32 v[6:7], s[26:27], v6, s62, v[0:1]
	s_lshl_b32 s94, s15, 7
	v_lshl_add_u64 v[6:7], v[6:7], 0, s[94:95]
	v_mov_b32_e32 v123, v2
	v_lshl_add_u64 v[6:7], v[6:7], 0, v[122:123]
	s_mov_b64 s[26:27], 0x1000
	v_lshl_add_u64 v[8:9], v[6:7], 0, s[26:27]
	global_load_dwordx4 v[12:15], v[8:9], off offset:16
	global_load_dwordx4 v[16:19], v[8:9], off offset:32
	s_movk_i32 s28, 0x1000
	v_add_co_u32_e32 v6, vcc, s28, v6
	v_mov_b32_e32 v121, v2
	s_nop 0
	v_addc_co_u32_e32 v7, vcc, 0, v7, vcc
	global_load_dwordx4 v[20:23], v[6:7], off
	global_load_dwordx4 v[24:27], v[116:117], off offset:16
	global_load_dwordx4 v[28:31], v[116:117], off
	global_load_dwordx4 v[32:35], v[8:9], off offset:48
	v_add_u32_e32 v6, s14, v137
	v_max_i32_e32 v10, s25, v6
	v_mad_i64_i32 v[6:7], s[26:27], v10, s62, v[0:1]
	v_mov_b32_e32 v125, v2
	v_or_b32_e32 v10, 1, v10
	v_lshl_add_u64 v[4:5], v[4:5], 0, v[120:121]
	v_lshl_add_u64 v[6:7], v[6:7], 0, s[94:95]
	v_mad_i64_i32 v[0:1], s[26:27], v10, s62, v[0:1]
	global_load_dwordx4 v[96:99], v[4:5], off offset:3072
	global_load_dwordx4 v[100:103], v[4:5], off offset:3136
	v_lshl_add_u64 v[4:5], v[6:7], 0, v[124:125]
	s_mov_b64 s[16:17], 0x1100
	v_lshl_add_u64 v[0:1], v[0:1], 0, s[94:95]
	v_lshl_add_u64 v[48:49], v[4:5], 0, s[16:17]
	v_add_co_u32_e32 v4, vcc, s28, v4
	v_lshl_add_u64 v[0:1], v[0:1], 0, v[124:125]
	s_nop 0
	v_addc_co_u32_e32 v5, vcc, 0, v5, vcc
	v_lshl_add_u64 v[50:51], v[0:1], 0, s[16:17]
	v_add_co_u32_e32 v0, vcc, s28, v0
	s_mov_b32 s14, 0xffff0000
	s_nop 0
	v_addc_co_u32_e32 v1, vcc, 0, v1, vcc
	global_load_dwordx4 v[4:7], v[4:5], off offset:256
	s_nop 0
	global_load_dwordx4 v[8:11], v[0:1], off offset:256
	v_readlane_b32 s16, v253, 11
	v_readlane_b32 s17, v253, 12
	v_mov_b32_e32 v129, v2
	s_mov_b64 s[70:71], 0
	s_movk_i32 s94, 0x220
	s_mov_b32 s18, 0x41800000
	s_mov_b32 s19, 0x41880000
	s_mov_b32 s20, 0x41900000
	s_mov_b32 s21, 0x41980000
	s_mov_b32 s22, 0x42000000
	s_waitcnt vmcnt(9)
	v_and_b32_e32 v53, 0xffff0000, v13
	v_and_b32_e32 v52, 0xffff0000, v12
	v_and_b32_e32 v57, 0xffff0000, v15
	v_and_b32_e32 v56, 0xffff0000, v14
	v_lshlrev_b32_e32 v1, 16, v13
	v_lshlrev_b32_e32 v0, 16, v12
	v_lshlrev_b32_e32 v55, 16, v15
	v_lshlrev_b32_e32 v54, 16, v14
	s_waitcnt vmcnt(8)
	v_and_b32_e32 v59, 0xffff0000, v16
	v_and_b32_e32 v61, 0xffff0000, v17
	v_pk_mul_f32 v[12:13], v[52:53], v[52:53]
	v_pk_mul_f32 v[14:15], v[56:57], v[56:57]
	v_lshlrev_b32_e32 v58, 16, v16
	v_lshlrev_b32_e32 v60, 16, v17
	v_lshlrev_b32_e32 v62, 16, v18
	v_and_b32_e32 v63, 0xffff0000, v18
	v_mul_f32_e32 v16, v59, v59
	v_mul_f32_e32 v18, v61, v61
	v_pk_fma_f32 v[12:13], v[0:1], v[0:1], v[12:13]
	v_pk_fma_f32 v[14:15], v[54:55], v[54:55], v[14:15]
	v_lshlrev_b32_e32 v64, 16, v19
	v_and_b32_e32 v65, 0xffff0000, v19
	v_pk_fma_f32 v[66:67], v[58:59], v[58:59], v[16:17] op_sel_hi:[1,1,0]
	v_pk_fma_f32 v[68:69], v[60:61], v[60:61], v[18:19] op_sel_hi:[1,1,0]
	v_pk_add_f32 v[72:73], v[12:13], v[12:13] op_sel:[0,1] op_sel_hi:[1,0]
	v_pk_add_f32 v[74:75], v[14:15], v[14:15] op_sel:[0,1] op_sel_hi:[1,0]
	global_load_dwordx4 v[12:15], v[116:117], off offset:48
	global_load_dwordx4 v[16:19], v[116:117], off offset:32
	v_mul_f32_e32 v36, v63, v63
	s_waitcnt vmcnt(9)
	v_and_b32_e32 v79, 0xffff0000, v23
	v_and_b32_e32 v81, 0xffff0000, v22
	v_pk_fma_f32 v[70:71], v[62:63], v[62:63], v[36:37] op_sel_hi:[1,1,0]
	v_lshlrev_b32_e32 v78, 16, v23
	v_lshlrev_b32_e32 v80, 16, v22
	v_mov_b32_e32 v36, v81
	v_mov_b32_e32 v37, v79
	v_mov_b32_e32 v22, v80
	v_mov_b32_e32 v23, v78
	v_pk_mul_f32 v[36:37], v[36:37], v[36:37]
	v_mul_f32_e32 v38, v65, v65
	v_pk_fma_f32 v[22:23], v[22:23], v[22:23], v[36:37]
	v_pk_fma_f32 v[76:77], v[64:65], v[64:65], v[38:39] op_sel_hi:[1,1,0]
	v_pk_add_f32 v[82:83], v[22:23], v[22:23] op_sel:[0,1] op_sel_hi:[1,0]
	v_lshlrev_b32_e32 v84, 16, v21
	v_and_b32_e32 v85, 0xffff0000, v21
	v_lshlrev_b32_e32 v86, 16, v20
	v_and_b32_e32 v87, 0xffff0000, v20
	global_load_dwordx4 v[20:23], v[116:117], off offset:80
	global_load_dwordx4 v[36:39], v[116:117], off offset:64
	v_mov_b32_e32 v42, v87
	v_mov_b32_e32 v43, v85
	v_mov_b32_e32 v40, v86
	v_mov_b32_e32 v41, v84
	v_pk_mul_f32 v[42:43], v[42:43], v[42:43]
	s_waitcnt vmcnt(8)
	v_lshlrev_b32_e32 v90, 16, v35
	v_pk_fma_f32 v[40:41], v[40:41], v[40:41], v[42:43]
	v_and_b32_e32 v91, 0xffff0000, v35
	v_pk_add_f32 v[88:89], v[40:41], v[40:41] op_sel:[0,1] op_sel_hi:[1,0]
	global_load_dwordx4 v[40:43], v[116:117], off offset:112
	global_load_dwordx4 v[44:47], v[116:117], off offset:96
	v_pk_mul_f32 v[92:93], v[90:91], v[90:91]
	s_nop 0
	v_mov_b32_e32 v71, v92
	v_mov_b32_e32 v77, v93
	v_pk_add_f32 v[70:71], v[70:71], v[76:77]
	v_lshlrev_b32_e32 v76, 16, v34
	v_and_b32_e32 v77, 0xffff0000, v34
	v_pk_mul_f32 v[34:35], v[76:77], v[76:77]
	s_nop 0
	v_mov_b32_e32 v67, v34
	v_mov_b32_e32 v69, v35
	v_pk_add_f32 v[34:35], v[66:67], v[68:69]
	v_lshlrev_b32_e32 v66, 16, v33
	v_pk_add_f32 v[34:35], v[34:35], v[70:71]
	v_and_b32_e32 v67, 0xffff0000, v33
	v_lshlrev_b32_e32 v70, 16, v32
	v_and_b32_e32 v71, 0xffff0000, v32
	v_pk_mul_f32 v[68:69], v[66:67], v[66:67]
	v_pk_mul_f32 v[32:33], v[70:71], v[70:71]
	v_mov_b32_e32 v73, v68
	v_mov_b32_e32 v75, v69
	v_mov_b32_e32 v89, v32
	v_mov_b32_e32 v83, v33
	v_pk_add_f32 v[68:69], v[72:73], v[74:75]
	v_pk_add_f32 v[32:33], v[88:89], v[82:83]
	s_nop 0
	v_pk_add_f32 v[32:33], v[32:33], v[68:69]
	v_mov_b32_e32 v68, v0
	v_pk_add_f32 v[32:33], v[32:33], v[34:35]
	v_mov_b32_e32 v69, v52
	v_add_f32_e32 v72, v32, v33
	global_load_dwordx4 v[32:35], v[48:49], off offset:16
	s_nop 0
	global_load_dwordx4 v[48:51], v[50:51], off offset:16
	ds_bpermute_b32 v73, v138, v72
	v_mov_b32_e32 v52, v1
	s_waitcnt lgkmcnt(0)
	v_add_f32_e32 v0, v72, v73
	v_fmamk_f32 v0, v0, 0x3c800000, v209
	v_mul_f32_e32 v1, 0x4b800000, v0
	v_cmp_gt_f32_e32 vcc, s68, v0
	s_nop 1
	v_cndmask_b32_e32 v0, v0, v1, vcc
	v_rsq_f32_e32 v72, v0
	v_mov_b32_e32 v0, v54
	v_mov_b32_e32 v1, v56
	v_mov_b32_e32 v56, v55
	v_mul_f32_e32 v54, 0x45800000, v72
	v_cndmask_b32_e32 v54, v72, v54, vcc
	v_pk_mul_f32 v[72:73], v[54:55], v[86:87] op_sel_hi:[0,1]
	v_pk_mul_f32 v[28:29], v[28:29], v[72:73]
	v_pk_mul_f32 v[72:73], v[54:55], v[84:85] op_sel_hi:[0,1]
	v_pk_mul_f32 v[30:31], v[30:31], v[72:73]
	v_cvt_pk_bf16_f32 v28, v28, v29
	v_cvt_pk_bf16_f32 v29, v30, v31
	v_pk_mul_f32 v[30:31], v[54:55], v[80:81] op_sel_hi:[0,1]
	v_pk_mul_f32 v[24:25], v[24:25], v[30:31]
	v_pk_mul_f32 v[0:1], v[54:55], v[0:1] op_sel_hi:[0,1]
	v_cvt_pk_bf16_f32 v30, v24, v25
	v_pk_mul_f32 v[24:25], v[54:55], v[78:79] op_sel_hi:[0,1]
	v_pk_mul_f32 v[24:25], v[26:27], v[24:25]
	s_waitcnt vmcnt(7)
	v_pk_mul_f32 v[0:1], v[12:13], v[0:1]
	v_cvt_pk_bf16_f32 v31, v24, v25
	v_pk_mul_f32 v[24:25], v[54:55], v[68:69] op_sel_hi:[0,1]
	s_waitcnt vmcnt(6)
	v_pk_mul_f32 v[16:17], v[16:17], v[24:25]
	v_pk_mul_f32 v[24:25], v[54:55], v[52:53] op_sel_hi:[0,1]
	v_pk_mul_f32 v[18:19], v[18:19], v[24:25]
	v_cvt_pk_bf16_f32 v16, v16, v17
	v_cvt_pk_bf16_f32 v17, v18, v19
	v_cvt_pk_bf16_f32 v18, v0, v1
	v_pk_mul_f32 v[0:1], v[54:55], v[56:57] op_sel_hi:[0,1]
	v_pk_mul_f32 v[0:1], v[14:15], v[0:1]
	ds_write_b128 v139, v[28:31]
	v_cvt_pk_bf16_f32 v19, v0, v1
	v_pk_mul_f32 v[0:1], v[54:55], v[58:59] op_sel_hi:[0,1]
	s_waitcnt vmcnt(4)
	v_pk_mul_f32 v[0:1], v[36:37], v[0:1]
	ds_write_b128 v139, v[16:19] offset:16
	v_cvt_pk_bf16_f32 v12, v0, v1
	v_pk_mul_f32 v[0:1], v[54:55], v[60:61] op_sel_hi:[0,1]
	v_pk_mul_f32 v[0:1], v[38:39], v[0:1]
	s_nop 0
	v_cvt_pk_bf16_f32 v13, v0, v1
	v_pk_mul_f32 v[0:1], v[54:55], v[62:63] op_sel_hi:[0,1]
	v_pk_mul_f32 v[0:1], v[20:21], v[0:1]
	s_nop 0
	v_cvt_pk_bf16_f32 v14, v0, v1
	v_pk_mul_f32 v[0:1], v[54:55], v[64:65] op_sel_hi:[0,1]
	v_pk_mul_f32 v[0:1], v[22:23], v[0:1]
	s_nop 0
	v_cvt_pk_bf16_f32 v15, v0, v1
	v_pk_mul_f32 v[0:1], v[54:55], v[70:71] op_sel_hi:[0,1]
	s_waitcnt vmcnt(2)
	v_pk_mul_f32 v[0:1], v[44:45], v[0:1]
	ds_write_b128 v139, v[12:15] offset:32
	v_cvt_pk_bf16_f32 v12, v0, v1
	v_pk_mul_f32 v[0:1], v[54:55], v[66:67] op_sel_hi:[0,1]
	v_pk_mul_f32 v[0:1], v[46:47], v[0:1]
	s_nop 0
	v_cvt_pk_bf16_f32 v13, v0, v1
	v_pk_mul_f32 v[0:1], v[54:55], v[76:77] op_sel_hi:[0,1]
	v_pk_mul_f32 v[0:1], v[40:41], v[0:1]
	s_nop 0
	v_cvt_pk_bf16_f32 v14, v0, v1
	v_pk_mul_f32 v[0:1], v[54:55], v[90:91] op_sel_hi:[0,1]
	v_pk_mul_f32 v[0:1], v[42:43], v[0:1]
	s_nop 0
	v_cvt_pk_bf16_f32 v15, v0, v1
	v_and_b32_e32 v0, 0xffff, v4
	v_lshrrev_b32_e32 v1, 16, v4
	v_lshl_or_b32 v0, v8, 16, v0
	v_and_or_b32 v1, v8, s14, v1
	v_and_b32_e32 v28, 1, v208
	v_lshlrev_b32_e32 v28, 4, v28
	v_xor_b32_e32 v28, v145, v28
	v_xor_b32_e32 v29, 8, v28
	v_add_u32_e32 v4, 0x9000, v28
	ds_write_b128 v139, v[12:15] offset:48
	ds_write2_b32 v4, v0, v1 offset1:136
	v_and_b32_e32 v0, 0xffff, v5
	v_lshrrev_b32_e32 v1, 16, v5
	v_lshl_or_b32 v0, v9, 16, v0
	v_and_or_b32 v1, v9, s14, v1
	v_add_u32_e32 v4, 0x9400, v28
	ds_write2_b32 v4, v0, v1 offset0:16 offset1:152
	v_and_b32_e32 v0, 0xffff, v6
	v_lshrrev_b32_e32 v1, 16, v6
	v_lshl_or_b32 v0, v10, 16, v0
	v_and_or_b32 v1, v10, s14, v1
	v_add_u32_e32 v4, 0x9800, v28
	ds_write2_b32 v4, v0, v1 offset0:32 offset1:168
	v_and_b32_e32 v0, 0xffff, v7
	v_lshrrev_b32_e32 v1, 16, v7
	v_lshl_or_b32 v0, v11, 16, v0
	v_and_or_b32 v1, v11, s14, v1
	v_add_u32_e32 v4, 0x9c00, v28
	ds_write2_b32 v4, v0, v1 offset0:48 offset1:184
	s_waitcnt vmcnt(1)
	v_and_b32_e32 v0, 0xffff, v32
	v_lshrrev_b32_e32 v1, 16, v32
	s_waitcnt vmcnt(0)
	v_lshl_or_b32 v0, v48, 16, v0
	v_and_or_b32 v1, v48, s14, v1
	v_add_u32_e32 v4, 0xa000, v29
	ds_write2_b32 v4, v0, v1 offset0:64 offset1:200
	v_and_b32_e32 v0, 0xffff, v33
	v_lshrrev_b32_e32 v1, 16, v33
	v_lshl_or_b32 v0, v49, 16, v0
	v_and_or_b32 v1, v49, s14, v1
	v_add_u32_e32 v4, 0xa400, v29
	ds_write2_b32 v4, v0, v1 offset0:80 offset1:216
	v_and_b32_e32 v0, 0xffff, v34
	v_lshrrev_b32_e32 v1, 16, v34
	v_lshl_or_b32 v0, v50, 16, v0
	v_and_or_b32 v1, v50, s14, v1
	v_add_u32_e32 v4, 0xa800, v29
	ds_write2_b32 v4, v0, v1 offset0:96 offset1:232
	v_and_b32_e32 v0, 0xffff, v35
	v_lshrrev_b32_e32 v1, 16, v35
	v_lshl_or_b32 v0, v51, 16, v0
	v_and_or_b32 v1, v51, s14, v1
	v_add_u32_e32 v4, 0xac00, v29
	ds_write2_b32 v4, v0, v1 offset0:112 offset1:248
	s_waitcnt lgkmcnt(0)
	s_barrier
	v_readfirstlane_b32 s32, v208
	s_cmp_lt_u32 s32, 0x100
	s_cbranch_scc1 .Lswa_stag
	s_sleep 44
